# align-barrier move also applied to the MLA-expansion GEMM instance (all three GEMM instances now run the leading half epilogue before its align barrier)
# baseline (speedup 1.0000x reference)
.LBB0_180:
	s_mov_b32 s98, 1
	s_lshl_b32 s7, s14, 1
	s_and_b32 s8, s7, 2
	s_ashr_i32 s7, s6, 31
	s_lshl_b64 s[6:7], s[6:7], 8
	s_cmp_lt_u32 s14, 2
	s_movk_i32 s9, 0x80
	s_cselect_b32 s79, 0xc0, s9
	s_mov_b32 s9, 0x25a00000
	s_cselect_b32 s9, s9, 0x27500000
	s_add_u32 s86, s60, s9
	s_addc_u32 s87, s61, 0
	s_mul_i32 s88, s8, 0x4800
	s_add_u32 s8, s6, s88
	s_addc_u32 s9, s7, 0
	v_mov_b32_e32 v0, v143
	s_mul_i32 s9, s9, s79
	s_mul_hi_u32 s10, s8, s79
	s_add_i32 s9, s10, s9
	v_and_or_b32 v145, v0, 15, s65
	s_mul_i32 s8, s8, s79
	v_mul_lo_u32 v145, s79, v145
	s_lshl_b64 s[8:9], s[8:9], 1
	v_lshlrev_b32_e32 v145, 1, v145
	v_and_b32_e32 v0, -16, v0
	s_add_u32 s8, s86, s8
	v_add3_u32 v0, v0, s70, v145
	s_addc_u32 s9, s87, s9
	v_lshl_add_u64 v[146:147], s[8:9], 0, v[0:1]
	v_cvt_pk_bf16_f32 v122, v122, v123
	v_cvt_pk_bf16_f32 v123, v124, v125
	v_cvt_pk_bf16_f32 v124, v126, v127
	v_cvt_pk_bf16_f32 v125, v128, v129
	global_store_dwordx4 v0, v[122:125], s[8:9]
	s_lshl_b32 s38, s79, 5
	s_lshl_b32 s8, s79, 6
	s_lshl_b32 s12, s79, 8
	s_addk_i32 s88, 0x4800
	v_cvt_pk_bf16_f32 v118, v118, v119
	v_cvt_pk_bf16_f32 v119, v120, v121
	v_cvt_pk_bf16_f32 v120, v114, v115
	v_lshl_add_u64 v[114:115], v[146:147], 0, s[38:39]
	s_mov_b32 s9, s39
	s_add_u32 s6, s6, s88
	v_cvt_pk_bf16_f32 v121, v116, v117
	global_store_dwordx4 v[114:115], v[118:121], off
	v_cvt_pk_bf16_f32 v110, v110, v111
	v_cvt_pk_bf16_f32 v111, v112, v113
	v_cvt_pk_bf16_f32 v112, v106, v107
	v_lshl_add_u64 v[106:107], v[146:147], 0, s[8:9]
	s_mul_i32 s10, s79, 0x60
	s_mov_b32 s11, s39
	s_addc_u32 s7, s7, 0
	v_cvt_pk_bf16_f32 v113, v108, v109
	global_store_dwordx4 v[106:107], v[110:113], off
	v_cvt_pk_bf16_f32 v102, v102, v103
	v_cvt_pk_bf16_f32 v103, v104, v105
	v_cvt_pk_bf16_f32 v104, v98, v99
	v_lshl_add_u64 v[98:99], v[146:147], 0, s[10:11]
	s_mov_b32 s13, s39
	s_mul_i32 s7, s7, s79
	s_mul_hi_u32 s88, s6, s79
	v_cvt_pk_bf16_f32 v105, v100, v101
	global_store_dwordx4 v[98:99], v[102:105], off
	v_cvt_pk_bf16_f32 v94, v94, v95
	v_cvt_pk_bf16_f32 v95, v96, v97
	v_cvt_pk_bf16_f32 v96, v90, v91
	v_lshl_add_u64 v[90:91], v[146:147], 0, s[12:13]
	s_mul_i32 s14, s79, 0x120
	s_mov_b32 s15, s39
	s_add_i32 s7, s88, s7
	s_mul_i32 s6, s6, s79
	v_cvt_pk_bf16_f32 v97, v92, v93
	global_store_dwordx4 v[90:91], v[94:97], off
	v_cvt_pk_bf16_f32 v86, v86, v87
	v_cvt_pk_bf16_f32 v87, v88, v89
	v_cvt_pk_bf16_f32 v88, v82, v83
	v_lshl_add_u64 v[82:83], v[146:147], 0, s[14:15]
	s_mul_i32 s16, s79, 0x140
	s_mov_b32 s17, s39
	s_lshl_b64 s[6:7], s[6:7], 1
	v_cvt_pk_bf16_f32 v89, v84, v85
	global_store_dwordx4 v[82:83], v[86:89], off
	v_cvt_pk_bf16_f32 v78, v78, v79
	v_cvt_pk_bf16_f32 v79, v80, v81
	v_cvt_pk_bf16_f32 v80, v74, v75
	v_lshl_add_u64 v[74:75], v[146:147], 0, s[16:17]
	s_mul_i32 s84, s79, 0x160
	s_mov_b32 s85, s39
	s_add_u32 s6, s86, s6
	v_cvt_pk_bf16_f32 v81, v76, v77
	global_store_dwordx4 v[74:75], v[78:81], off
	v_cvt_pk_bf16_f32 v70, v70, v71
	v_cvt_pk_bf16_f32 v71, v72, v73
	v_cvt_pk_bf16_f32 v72, v66, v67
	v_lshl_add_u64 v[66:67], v[146:147], 0, s[84:85]
	s_addc_u32 s7, s87, s7
	v_cvt_pk_bf16_f32 v73, v68, v69
	global_store_dwordx4 v[66:67], v[70:73], off
	v_lshl_add_u64 v[66:67], s[6:7], 0, v[0:1]
	v_cvt_pk_bf16_f32 v62, v62, v63
	v_cvt_pk_bf16_f32 v63, v64, v65
	v_cvt_pk_bf16_f32 v64, v58, v59
	v_cvt_pk_bf16_f32 v65, v60, v61
	global_store_dwordx4 v0, v[62:65], s[6:7]
	v_cvt_pk_bf16_f32 v54, v54, v55
	v_cvt_pk_bf16_f32 v55, v56, v57
	v_cvt_pk_bf16_f32 v56, v50, v51
	v_lshl_add_u64 v[50:51], v[66:67], 0, s[38:39]
	v_cvt_pk_bf16_f32 v57, v52, v53
	global_store_dwordx4 v[50:51], v[54:57], off
	v_cvt_pk_bf16_f32 v46, v46, v47
	v_cvt_pk_bf16_f32 v47, v48, v49
	v_cvt_pk_bf16_f32 v48, v42, v43
	v_lshl_add_u64 v[42:43], v[66:67], 0, s[8:9]
	v_cvt_pk_bf16_f32 v49, v44, v45
	global_store_dwordx4 v[42:43], v[46:49], off
	v_cvt_pk_bf16_f32 v38, v38, v39
	v_cvt_pk_bf16_f32 v39, v40, v41
	v_cvt_pk_bf16_f32 v40, v34, v35
	v_lshl_add_u64 v[34:35], v[66:67], 0, s[10:11]
	v_cvt_pk_bf16_f32 v41, v36, v37
	global_store_dwordx4 v[34:35], v[38:41], off
	v_cvt_pk_bf16_f32 v30, v30, v31
	v_cvt_pk_bf16_f32 v31, v32, v33
	v_cvt_pk_bf16_f32 v32, v26, v27
	v_lshl_add_u64 v[26:27], v[66:67], 0, s[12:13]
	v_cvt_pk_bf16_f32 v33, v28, v29
	global_store_dwordx4 v[26:27], v[30:33], off
	v_cvt_pk_bf16_f32 v22, v22, v23
	v_cvt_pk_bf16_f32 v23, v24, v25
	v_cvt_pk_bf16_f32 v24, v18, v19
	v_lshl_add_u64 v[18:19], v[66:67], 0, s[14:15]
	v_cvt_pk_bf16_f32 v25, v20, v21
	global_store_dwordx4 v[18:19], v[22:25], off
	v_cvt_pk_bf16_f32 v14, v14, v15
	v_cvt_pk_bf16_f32 v15, v16, v17
	v_cvt_pk_bf16_f32 v16, v10, v11
	v_lshl_add_u64 v[10:11], v[66:67], 0, s[16:17]
	v_cvt_pk_bf16_f32 v17, v12, v13
	global_store_dwordx4 v[10:11], v[14:17], off
	v_cvt_pk_bf16_f32 v6, v6, v7
	v_cvt_pk_bf16_f32 v7, v8, v9
	v_cvt_pk_bf16_f32 v8, v2, v3
	v_lshl_add_u64 v[2:3], v[66:67], 0, s[84:85]
	s_and_b64 vcc, exec, s[40:41]
	s_mov_b64 s[6:7], -1
	s_mov_b32 s79, 0x24000
	s_mov_b32 s84, 0x49000
	s_mov_b32 s85, 0x6d000
	v_cvt_pk_bf16_f32 v9, v4, v5
	global_store_dwordx4 v[2:3], v[6:9], off
	s_cmp_lg_u64 s[46:47], 0
	s_cbranch_scc1 .Lalign2_skip
	s_barrier
.Lalign2_skip:
	s_cbranch_vccnz .LBB0_168
	s_andn2_b64 vcc, exec, s[46:47]
	s_cbranch_vccnz .LBB0_167
	s_barrier
	s_branch .LBB0_167
